# i/f-gate GEMM loop: drop the four dead LDS-DMA loads of the unused column half per iteration; counted waits re-derived (vmcnt 8 -> 6)
# speedup vs baseline: 1.0120x; 1.0120x over previous
; #define PG8_STAGE(bufoff, gbase, voff) do { _Pragma("unroll") for (int _i = 0; _i < 2; ++_i) \
;         __builtin_amdgcn_global_load_lds((const unsigned*)((const char*)(gbase) + (voff)[_i]), (PG8_LAS unsigned*)(lds + (bufoff) + ldsw + _i * 8192), 16, 0, 0); } while (0)
; #define PG8_LDA(dst, b, h) do { _Pragma("unroll") for (int m = 0; m < 4; ++m) _Pragma("unroll") for (int k = 0; k < 2; ++k) dst[m][k] = *(const PG8_LAS bf16x8*)(lds + PG8_SA(b, h) + aoff + m * 2048 + k * 1024); } while (0)
; #define PG8_LDB(dst, b, h) do { _Pragma("unroll") for (int n = 0; n < 2; ++n) _Pragma("unroll") for (int k = 0; k < 2; ++k) dst[n][k] = *(const PG8_LAS bf16x8*)(lds + PG8_SB(b, h) + boff + n * 2048 + k * 1024); } while (0)
; #define PG8_MMA(ai, bj, At, Bt) do { __builtin_amdgcn_s_setprio(1); _Pragma("unroll") for (int m = 0; m < 4; ++m) _Pragma("unroll") for (int n = 0; n < 2; ++n) _Pragma("unroll") for (int k = 0; k < 2; ++k) \
;         acc[ai][bj][m][n] = __builtin_amdgcn_mfma_f32_16x16x32_bf16(Bt[n][k], At[m][k], acc[ai][bj][m][n], 0, 0, 0); __builtin_amdgcn_s_setprio(0); } while (0)
; #define PG8_BAR __builtin_amdgcn_s_barrier()
; template <class Epi, class Sched, bool ALIGN_EPI = false, bool SP2 = false>
; __device__ __forceinline__ void gemm_phase(PG8_LAS unsigned char* lds, const Gemm g, const Sched& S, const Epi& E) {
;     ...
;             if constexpr (SP2) {
;             PG8_LDB(B0, 0, 0); PG8_LDB(B1, 0, 1); PG8_SCHED; PG8_LDA(At, 0, 0); PG8_STAGE(PG8_SA(1, 1), a1 + hstep, voffA);
;             PG8_WAIT_V(8); PG8_WAIT_L(0); PG8_BAR; PG8_MMA(0, 0, At, B0); PG8_MMA(0, 1, At, B1); PG8_BAR; PG8_SCHED;
;             PG8_LDA(At, 0, 1); PG8_STAGE(PG8_SB(0, 0), b2, voffB); PG8_STAGE(PG8_SB(0, 1), b2 + hstep, voffB); PG8_STAGE(PG8_SA(0, 0), a2, voffA);
;             PG8_WAIT_V(8); PG8_WAIT_L(0); PG8_BAR; PG8_MMA(1, 0, At, B0); PG8_MMA(1, 1, At, B1); PG8_BAR; PG8_SCHED;
;             PG8_LDB(B0, 1, 0); PG8_LDB(B1, 1, 1); PG8_SCHED; PG8_LDA(At, 1, 0); PG8_STAGE(PG8_SA(0, 1), a2 + hstep, voffA);
;             PG8_WAIT_V(8); PG8_WAIT_L(0); PG8_BAR; PG8_MMA(0, 0, At, B0); PG8_MMA(0, 1, At, B1); PG8_BAR; PG8_SCHED;
;             PG8_LDA(At, 1, 1); PG8_STAGE(PG8_SB(1, 0), b3, voffB); PG8_STAGE(PG8_SB(1, 1), b3 + hstep, voffB); PG8_STAGE(PG8_SA(1, 0), a3, voffA);
;             PG8_WAIT_V(8); PG8_WAIT_L(0); PG8_BAR; PG8_MMA(1, 0, At, B0); PG8_MMA(1, 1, At, B1); PG8_BAR; PG8_SCHED;
.LBB0_229:
	s_add_u32 s22, s20, 0xfffc0080
	s_addc_u32 s23, s21, -1
	s_add_i32 s47, 0, 0x10000
	v_add_u32_e32 v88, s47, v91
	ds_read_b128 v[18:21], v88
	ds_read_b128 v[22:25], v88 offset:1024
	ds_read_b128 v[94:97], v88 offset:2048
	ds_read_b128 v[98:101], v88 offset:3072
	s_cmp_eq_u32 s46, 12
	s_cselect_b32 s25, s15, s23
	s_cselect_b32 s24, s42, s22
	s_cselect_b32 s23, s9, s45
	s_cselect_b32 s22, s43, s44
	v_lshl_add_u64 v[88:89], s[20:21], 0, v[84:85]
	s_add_i32 m0, s29, 0xc000
	ds_read_b128 v[102:105], v92
	ds_read_b128 v[106:109], v92 offset:1024
	ds_read_b128 v[110:113], v92 offset:2048
	ds_read_b128 v[114:117], v92 offset:3072
	ds_read_b128 v[118:121], v92 offset:4096
	ds_read_b128 v[122:125], v92 offset:5120
	ds_read_b128 v[126:129], v92 offset:6144
	ds_read_b128 v[130:133], v92 offset:7168
	global_load_lds_dwordx4 v[88:89], off
	v_lshl_add_u64 v[88:89], s[20:21], 0, v[86:87]
	s_add_i32 m0, s29, 0xe000
	s_nop 0
	global_load_lds_dwordx4 v[88:89], off
	s_waitcnt vmcnt(6)
	s_waitcnt lgkmcnt(0)
	s_barrier
	s_setprio 1
	s_waitcnt lgkmcnt(0)
	v_mfma_f32_16x16x32_bf16 v[70:73], v[18:21], v[102:105], v[70:73]
	v_mfma_f32_16x16x32_bf16 v[66:69], v[94:97], v[102:105], v[66:69]
	v_mfma_f32_16x16x32_bf16 v[62:65], v[18:21], v[110:113], v[62:65]
	v_mfma_f32_16x16x32_bf16 v[58:61], v[94:97], v[110:113], v[58:61]
	v_mfma_f32_16x16x32_bf16 v[54:57], v[18:21], v[118:121], v[54:57]
	v_mfma_f32_16x16x32_bf16 v[50:53], v[94:97], v[118:121], v[50:53]
	v_mfma_f32_16x16x32_bf16 v[46:49], v[18:21], v[126:129], v[46:49]
	v_mfma_f32_16x16x32_bf16 v[42:45], v[94:97], v[126:129], v[42:45]
	v_mfma_f32_16x16x32_bf16 v[70:73], v[22:25], v[106:109], v[70:73]
	v_mfma_f32_16x16x32_bf16 v[66:69], v[98:101], v[106:109], v[66:69]
	v_mfma_f32_16x16x32_bf16 v[62:65], v[22:25], v[114:117], v[62:65]
	v_mfma_f32_16x16x32_bf16 v[58:61], v[98:101], v[114:117], v[58:61]
	v_mfma_f32_16x16x32_bf16 v[54:57], v[22:25], v[122:125], v[54:57]
	v_mfma_f32_16x16x32_bf16 v[50:53], v[98:101], v[122:125], v[50:53]
	v_mfma_f32_16x16x32_bf16 v[46:49], v[22:25], v[130:133], v[46:49]
	v_mfma_f32_16x16x32_bf16 v[42:45], v[98:101], v[130:133], v[42:45]
	s_setprio 0
	s_setprio 1
	s_setprio 0
	s_barrier
	s_add_i32 s47, s47, s28
	v_lshl_add_u64 v[88:89], s[22:23], 0, v[78:79]
	s_mov_b32 m0, s47
	ds_read_b128 v[102:105], v92 offset:16384
	ds_read_b128 v[106:109], v92 offset:17408
	ds_read_b128 v[110:113], v92 offset:18432
	ds_read_b128 v[114:117], v92 offset:19456
	ds_read_b128 v[118:121], v92 offset:20480
	ds_read_b128 v[122:125], v92 offset:21504
	ds_read_b128 v[126:129], v92 offset:22528
	ds_read_b128 v[130:133], v92 offset:23552
	global_load_lds_dwordx4 v[88:89], off
	s_add_i32 m0, s47, 0x2000
	s_add_u32 s48, s22, 0x40000
	v_lshl_add_u64 v[134:135], s[22:23], 0, v[74:75]
	s_addc_u32 s49, s23, 0
	global_load_lds_dwordx4 v[134:135], off
	v_lshl_add_u64 v[136:137], s[48:49], 0, v[78:79]
	s_mov_b32 m0, s30
	v_lshl_add_u64 v[138:139], s[24:25], 0, v[76:77]
	v_lshl_add_u64 v[136:137], s[48:49], 0, v[74:75]
	s_mov_b32 m0, s31
	s_nop 0
	v_lshl_add_u64 v[136:137], s[24:25], 0, v[0:1]
	s_mov_b32 m0, s29
	s_nop 0
	global_load_lds_dwordx4 v[136:137], off
	s_mov_b32 m0, s33
	s_nop 0
	global_load_lds_dwordx4 v[138:139], off
	s_waitcnt vmcnt(6)
	s_waitcnt lgkmcnt(0)
	s_barrier
	s_setprio 1
	s_waitcnt lgkmcnt(0)
	v_mfma_f32_16x16x32_bf16 v[38:41], v[18:21], v[102:105], v[38:41]
	v_mfma_f32_16x16x32_bf16 v[34:37], v[94:97], v[102:105], v[34:37]
	v_mfma_f32_16x16x32_bf16 v[30:33], v[18:21], v[110:113], v[30:33]
	v_mfma_f32_16x16x32_bf16 v[26:29], v[94:97], v[110:113], v[26:29]
	v_mfma_f32_16x16x32_bf16 v[14:17], v[18:21], v[118:121], v[14:17]
	v_mfma_f32_16x16x32_bf16 v[10:13], v[94:97], v[118:121], v[10:13]
	v_mfma_f32_16x16x32_bf16 v[6:9], v[18:21], v[126:129], v[6:9]
	v_mfma_f32_16x16x32_bf16 v[2:5], v[94:97], v[126:129], v[2:5]
	v_mfma_f32_16x16x32_bf16 v[38:41], v[22:25], v[106:109], v[38:41]
	v_mfma_f32_16x16x32_bf16 v[34:37], v[98:101], v[106:109], v[34:37]
	v_mfma_f32_16x16x32_bf16 v[30:33], v[22:25], v[114:117], v[30:33]
	v_mfma_f32_16x16x32_bf16 v[26:29], v[98:101], v[114:117], v[26:29]
	v_mfma_f32_16x16x32_bf16 v[14:17], v[22:25], v[122:125], v[14:17]
	v_mfma_f32_16x16x32_bf16 v[10:13], v[98:101], v[122:125], v[10:13]
	v_mfma_f32_16x16x32_bf16 v[6:9], v[22:25], v[130:133], v[6:9]
	v_mfma_f32_16x16x32_bf16 v[2:5], v[98:101], v[130:133], v[2:5]
	s_setprio 0
	s_setprio 1
	s_setprio 0
	s_barrier
; #define PG8_STAGE(bufoff, gbase, voff) do { _Pragma("unroll") for (int _i = 0; _i < 2; ++_i) \
;         __builtin_amdgcn_global_load_lds((const unsigned*)((const char*)(gbase) + (voff)[_i]), (PG8_LAS unsigned*)(lds + (bufoff) + ldsw + _i * 8192), 16, 0, 0); } while (0)
; #define PG8_LDA(dst, b, h) do { _Pragma("unroll") for (int m = 0; m < 4; ++m) _Pragma("unroll") for (int k = 0; k < 2; ++k) dst[m][k] = *(const PG8_LAS bf16x8*)(lds + PG8_SA(b, h) + aoff + m * 2048 + k * 1024); } while (0)
; #define PG8_LDB(dst, b, h) do { _Pragma("unroll") for (int n = 0; n < 2; ++n) _Pragma("unroll") for (int k = 0; k < 2; ++k) dst[n][k] = *(const PG8_LAS bf16x8*)(lds + PG8_SB(b, h) + boff + n * 2048 + k * 1024); } while (0)
; #define PG8_MMA(ai, bj, At, Bt) do { __builtin_amdgcn_s_setprio(1); _Pragma("unroll") for (int m = 0; m < 4; ++m) _Pragma("unroll") for (int n = 0; n < 2; ++n) _Pragma("unroll") for (int k = 0; k < 2; ++k) \
;         acc[ai][bj][m][n] = __builtin_amdgcn_mfma_f32_16x16x32_bf16(Bt[n][k], At[m][k], acc[ai][bj][m][n], 0, 0, 0); __builtin_amdgcn_s_setprio(0); } while (0)
; #define PG8_BAR __builtin_amdgcn_s_barrier()
; template <class Epi, class Sched, bool ALIGN_EPI = false, bool SP2 = false>
; __device__ __forceinline__ void gemm_phase(PG8_LAS unsigned char* lds, const Gemm g, const Sched& S, const Epi& E) {
;     ...
;             if constexpr (SP2) {
;             PG8_LDB(B0, 0, 0); PG8_LDB(B1, 0, 1); PG8_SCHED; PG8_LDA(At, 0, 0); PG8_STAGE(PG8_SA(1, 1), a1 + hstep, voffA);
;             PG8_WAIT_V(8); PG8_WAIT_L(0); PG8_BAR; PG8_MMA(0, 0, At, B0); PG8_MMA(0, 1, At, B1); PG8_BAR; PG8_SCHED;
;             PG8_LDA(At, 0, 1); PG8_STAGE(PG8_SB(0, 0), b2, voffB); PG8_STAGE(PG8_SB(0, 1), b2 + hstep, voffB); PG8_STAGE(PG8_SA(0, 0), a2, voffA);
;             PG8_WAIT_V(8); PG8_WAIT_L(0); PG8_BAR; PG8_MMA(1, 0, At, B0); PG8_MMA(1, 1, At, B1); PG8_BAR; PG8_SCHED;
;             PG8_LDB(B0, 1, 0); PG8_LDB(B1, 1, 1); PG8_SCHED; PG8_LDA(At, 1, 0); PG8_STAGE(PG8_SA(0, 1), a2 + hstep, voffA);
;             PG8_WAIT_V(8); PG8_WAIT_L(0); PG8_BAR; PG8_MMA(0, 0, At, B0); PG8_MMA(0, 1, At, B1); PG8_BAR; PG8_SCHED;
;             PG8_LDA(At, 1, 1); PG8_STAGE(PG8_SB(1, 0), b3, voffB); PG8_STAGE(PG8_SB(1, 1), b3 + hstep, voffB); PG8_STAGE(PG8_SA(1, 0), a3, voffA);
;             PG8_WAIT_V(8); PG8_WAIT_L(0); PG8_BAR; PG8_MMA(1, 0, At, B0); PG8_MMA(1, 1, At, B1); PG8_BAR; PG8_SCHED;
	s_add_i32 s47, 0, 0x18000
	v_add_u32_e32 v93, s47, v91
	ds_read_b128 v[18:21], v93
	ds_read_b128 v[22:25], v93 offset:1024
	ds_read_b128 v[94:97], v93 offset:2048
	ds_read_b128 v[98:101], v93 offset:3072
	s_add_u32 s24, s24, 0x40000
	s_addc_u32 s25, s25, 0
	s_mov_b32 m0, s34
	v_lshl_add_u64 v[140:141], s[24:25], 0, v[0:1]
	ds_read_b128 v[102:105], v92 offset:32768
	ds_read_b128 v[106:109], v92 offset:33792
	ds_read_b128 v[110:113], v92 offset:34816
	ds_read_b128 v[114:117], v92 offset:35840
	ds_read_b128 v[118:121], v92 offset:36864
	ds_read_b128 v[122:125], v92 offset:37888
	ds_read_b128 v[126:129], v92 offset:38912
	ds_read_b128 v[130:133], v92 offset:39936
	global_load_lds_dwordx4 v[140:141], off
	v_lshl_add_u64 v[140:141], s[24:25], 0, v[76:77]
	s_mov_b32 m0, s35
	s_nop 0
	global_load_lds_dwordx4 v[140:141], off
	s_waitcnt vmcnt(6)
	s_waitcnt lgkmcnt(0)
	s_barrier
	s_setprio 1
	s_waitcnt lgkmcnt(0)
	v_mfma_f32_16x16x32_bf16 v[70:73], v[18:21], v[102:105], v[70:73]
	v_mfma_f32_16x16x32_bf16 v[66:69], v[94:97], v[102:105], v[66:69]
	v_mfma_f32_16x16x32_bf16 v[62:65], v[18:21], v[110:113], v[62:65]
	v_mfma_f32_16x16x32_bf16 v[58:61], v[94:97], v[110:113], v[58:61]
	v_mfma_f32_16x16x32_bf16 v[54:57], v[18:21], v[118:121], v[54:57]
	v_mfma_f32_16x16x32_bf16 v[50:53], v[94:97], v[118:121], v[50:53]
	v_mfma_f32_16x16x32_bf16 v[46:49], v[18:21], v[126:129], v[46:49]
	v_mfma_f32_16x16x32_bf16 v[42:45], v[94:97], v[126:129], v[42:45]
	v_mfma_f32_16x16x32_bf16 v[70:73], v[22:25], v[106:109], v[70:73]
	v_mfma_f32_16x16x32_bf16 v[66:69], v[98:101], v[106:109], v[66:69]
	v_mfma_f32_16x16x32_bf16 v[62:65], v[22:25], v[114:117], v[62:65]
	v_mfma_f32_16x16x32_bf16 v[58:61], v[98:101], v[114:117], v[58:61]
	v_mfma_f32_16x16x32_bf16 v[54:57], v[22:25], v[122:125], v[54:57]
	v_mfma_f32_16x16x32_bf16 v[50:53], v[98:101], v[122:125], v[50:53]
	v_mfma_f32_16x16x32_bf16 v[46:49], v[22:25], v[130:133], v[46:49]
	v_mfma_f32_16x16x32_bf16 v[42:45], v[98:101], v[130:133], v[42:45]
	s_setprio 0
	s_setprio 1
	s_setprio 0
	s_barrier
	s_add_i32 s24, s47, s28
	v_lshl_add_u64 v[88:89], v[88:89], 0, s[84:85]
	s_mov_b32 m0, s24
	ds_read_b128 v[102:105], v92 offset:49152
	ds_read_b128 v[106:109], v92 offset:50176
	ds_read_b128 v[110:113], v92 offset:51200
	ds_read_b128 v[114:117], v92 offset:52224
	ds_read_b128 v[118:121], v92 offset:53248
	ds_read_b128 v[122:125], v92 offset:54272
	ds_read_b128 v[126:129], v92 offset:55296
	ds_read_b128 v[130:133], v92 offset:56320
	global_load_lds_dwordx4 v[88:89], off
	s_add_i32 m0, s24, 0x2000
	s_add_u32 s22, s22, 0x40080
	v_lshl_add_u64 v[88:89], v[134:135], 0, s[84:85]
	s_addc_u32 s23, s23, 0
	global_load_lds_dwordx4 v[88:89], off
	v_lshl_add_u64 v[88:89], s[22:23], 0, v[78:79]
	s_mov_b32 m0, s38
	s_nop 0
	v_lshl_add_u64 v[88:89], s[22:23], 0, v[74:75]
	s_mov_b32 m0, s39
	s_nop 0
	v_lshl_add_u64 v[88:89], v[136:137], 0, s[84:85]
	s_mov_b32 m0, s36
	s_nop 0
	global_load_lds_dwordx4 v[88:89], off
	v_lshl_add_u64 v[88:89], v[138:139], 0, s[84:85]
	s_mov_b32 m0, s37
	s_nop 0
	global_load_lds_dwordx4 v[88:89], off
	s_waitcnt vmcnt(6)
	s_waitcnt lgkmcnt(0)
	s_barrier
	s_setprio 1
	s_waitcnt lgkmcnt(0)
	v_mfma_f32_16x16x32_bf16 v[38:41], v[18:21], v[102:105], v[38:41]
	v_mfma_f32_16x16x32_bf16 v[34:37], v[94:97], v[102:105], v[34:37]
	v_mfma_f32_16x16x32_bf16 v[30:33], v[18:21], v[110:113], v[30:33]
	v_mfma_f32_16x16x32_bf16 v[26:29], v[94:97], v[110:113], v[26:29]
	v_mfma_f32_16x16x32_bf16 v[14:17], v[18:21], v[118:121], v[14:17]
	v_mfma_f32_16x16x32_bf16 v[10:13], v[94:97], v[118:121], v[10:13]
	v_mfma_f32_16x16x32_bf16 v[6:9], v[18:21], v[126:129], v[6:9]
	v_mfma_f32_16x16x32_bf16 v[2:5], v[94:97], v[126:129], v[2:5]
	v_mfma_f32_16x16x32_bf16 v[38:41], v[22:25], v[106:109], v[38:41]
	v_mfma_f32_16x16x32_bf16 v[34:37], v[98:101], v[106:109], v[34:37]
	v_mfma_f32_16x16x32_bf16 v[30:33], v[22:25], v[114:117], v[30:33]
	v_mfma_f32_16x16x32_bf16 v[26:29], v[98:101], v[114:117], v[26:29]
	v_mfma_f32_16x16x32_bf16 v[14:17], v[22:25], v[122:125], v[14:17]
	v_mfma_f32_16x16x32_bf16 v[10:13], v[98:101], v[122:125], v[10:13]
	v_mfma_f32_16x16x32_bf16 v[6:9], v[22:25], v[130:133], v[6:9]
	v_mfma_f32_16x16x32_bf16 v[2:5], v[98:101], v[130:133], v[2:5]
	s_setprio 0
	s_setprio 1
	s_setprio 0
	s_barrier
	s_add_i32 s46, s46, 2
	s_add_u32 s20, s20, 0x100
	s_addc_u32 s21, s21, 0
	s_add_u32 s44, s44, 0x100
	s_addc_u32 s45, s45, 0
	s_cmp_gt_u32 s46, 13
	s_cbranch_scc0 .LBB0_229
	s_and_b64 vcc, exec, s[10:11]
	s_cbranch_vccz .LBB0_232
	s_barrier
